# speedup vs baseline: 1.0110x; 1.0034x over previous
; __device__ void phase_ln(const Params& p) {
;   constexpr float ALPHA = 1.189207115002721f;
;   const int wid = threadIdx.x >> 6, lane = threadIdx.x & 63;
;   for (int row = blockIdx.x * 8 + wid; row < T; row += gridDim.x * 8) {
;     const float* xr = p.x + (long)row * DM; const bf16* hr = p.xb + (long)row * DM; float* r = p.out + (long)row * DM;
;     f32x4 v[16]; float s = 0.f;
; #pragma unroll
;     for (int i = 0; i < 16; ++i) { const f32x4 xv = __builtin_nontemporal_load(reinterpret_cast<const f32x4*>(xr + i * 256 + lane * 4));
;       const u32x2 hw = __builtin_nontemporal_load(reinterpret_cast<const u32x2*>(hr + i * 256 + lane * 4));
;       v[i][0] = fmaf(ALPHA, xv[0], __uint_as_float(hw[0] << 16)); v[i][1] = fmaf(ALPHA, xv[1], __uint_as_float(hw[0] & 0xffff0000u));
;       v[i][2] = fmaf(ALPHA, xv[2], __uint_as_float(hw[1] << 16)); v[i][3] = fmaf(ALPHA, xv[3], __uint_as_float(hw[1] & 0xffff0000u));
;       s += v[i][0] + v[i][1] + v[i][2] + v[i][3]; }
.LBB0_450:
	s_cmp_lg_u32 s80, 5
	v_readlane_b32 s2, v252, 36
	s_cselect_b64 s[0:1], -1, 0
	v_readlane_b32 s3, v252, 37
	s_and_b64 s[0:1], s[2:3], s[0:1]
	s_and_b64 vcc, exec, s[0:1]
	s_cbranch_vccnz .LBB0_454
	v_readlane_b32 s2, v252, 34
	v_readlane_b32 s3, v252, 35
	v_readlane_b32 s4, v252, 0
	v_readlane_b32 s8, v252, 2
	v_readlane_b32 s9, v252, 3
	v_bfe_u32 v1, v0, 6, 4
	s_load_dword s5, s[2:3], 0x130
	v_mbcnt_lo_u32_b32 v2, -1, 0
	v_readfirstlane_b32 s6, v1
	v_mbcnt_hi_u32_b32 v2, -1, v2
	s_lshl_b32 s4, s4, 3
	s_add_u32 s4, s4, s6
	s_mov_b32 s7, 0x3f9837f0
	v_lshlrev_b32_e32 v240, 4, v2
	v_lshlrev_b32_e32 v244, 3, v2
	v_add_u32_e32 v241, 0x1000, v240
	v_add_u32_e32 v242, 0x2000, v240
	v_add_u32_e32 v243, 0x3000, v240
	v_add_u32_e32 v245, 0x800, v244
	v_add_u32_e32 v246, 0x1000, v244
	v_add_u32_e32 v247, 0x1800, v244
	v_mov_b32_e32 v104, 0x3727c5ac
	global_load_dwordx4 v[112:115], v240, s[30:31] offset:0
	global_load_dwordx4 v[116:119], v240, s[30:31] offset:1024
	global_load_dwordx4 v[120:123], v240, s[30:31] offset:2048
	global_load_dwordx4 v[124:127], v240, s[30:31] offset:3072
	global_load_dwordx4 v[128:131], v241, s[30:31] offset:0
	global_load_dwordx4 v[132:135], v241, s[30:31] offset:1024
	global_load_dwordx4 v[136:139], v241, s[30:31] offset:2048
	global_load_dwordx4 v[140:143], v241, s[30:31] offset:3072
	global_load_dwordx4 v[144:147], v242, s[30:31] offset:0
	global_load_dwordx4 v[148:151], v242, s[30:31] offset:1024
	global_load_dwordx4 v[152:155], v242, s[30:31] offset:2048
	global_load_dwordx4 v[156:159], v242, s[30:31] offset:3072
	global_load_dwordx4 v[160:163], v243, s[30:31] offset:0
	global_load_dwordx4 v[164:167], v243, s[30:31] offset:1024
	global_load_dwordx4 v[168:171], v243, s[30:31] offset:2048
	global_load_dwordx4 v[172:175], v243, s[30:31] offset:3072
	global_load_dwordx4 v[176:179], v240, s[36:37] offset:0
	global_load_dwordx4 v[180:183], v240, s[36:37] offset:1024
	global_load_dwordx4 v[184:187], v240, s[36:37] offset:2048
	global_load_dwordx4 v[188:191], v240, s[36:37] offset:3072
	global_load_dwordx4 v[192:195], v241, s[36:37] offset:0
	global_load_dwordx4 v[196:199], v241, s[36:37] offset:1024
	global_load_dwordx4 v[200:203], v241, s[36:37] offset:2048
	global_load_dwordx4 v[204:207], v241, s[36:37] offset:3072
	global_load_dwordx4 v[208:211], v242, s[36:37] offset:0
	global_load_dwordx4 v[212:215], v242, s[36:37] offset:1024
	global_load_dwordx4 v[216:219], v242, s[36:37] offset:2048
	global_load_dwordx4 v[220:223], v242, s[36:37] offset:3072
	global_load_dwordx4 v[224:227], v243, s[36:37] offset:0
	global_load_dwordx4 v[228:231], v243, s[36:37] offset:1024
	global_load_dwordx4 v[232:235], v243, s[36:37] offset:2048
	global_load_dwordx4 v[236:239], v243, s[36:37] offset:3072
	s_waitcnt lgkmcnt(0)
	s_lshl_b32 s5, s5, 3
	s_cmpk_lt_u32 s4, 0x4000
	s_cbranch_scc0 .LBB0_454
	s_waitcnt vmcnt(8)
.Lln_row:
	s_lshl_b32 s10, s4, 14
	s_lshl_b32 s11, s4, 13
	s_add_u32 s12, s8, s10
	s_addc_u32 s13, s9, 0
	s_add_u32 s14, s38, s10
	s_addc_u32 s15, s39, 0
	s_add_u32 s16, s40, s11
	s_addc_u32 s17, s41, 0
	global_load_dwordx4 v[0:3], v240, s[12:13] offset:0 nt
	global_load_dwordx2 v[64:65], v244, s[16:17] offset:0 nt
	global_load_dwordx4 v[4:7], v240, s[12:13] offset:1024 nt
	global_load_dwordx2 v[66:67], v244, s[16:17] offset:512 nt
	global_load_dwordx4 v[8:11], v240, s[12:13] offset:2048 nt
	global_load_dwordx2 v[68:69], v244, s[16:17] offset:1024 nt
	global_load_dwordx4 v[12:15], v240, s[12:13] offset:3072 nt
	global_load_dwordx2 v[70:71], v244, s[16:17] offset:1536 nt
	global_load_dwordx4 v[16:19], v241, s[12:13] offset:0 nt
	global_load_dwordx2 v[72:73], v245, s[16:17] offset:0 nt
	global_load_dwordx4 v[20:23], v241, s[12:13] offset:1024 nt
	global_load_dwordx2 v[74:75], v245, s[16:17] offset:512 nt
	global_load_dwordx4 v[24:27], v241, s[12:13] offset:2048 nt
	global_load_dwordx2 v[76:77], v245, s[16:17] offset:1024 nt
	global_load_dwordx4 v[28:31], v241, s[12:13] offset:3072 nt
	global_load_dwordx2 v[78:79], v245, s[16:17] offset:1536 nt
	global_load_dwordx4 v[32:35], v242, s[12:13] offset:0 nt
	global_load_dwordx2 v[80:81], v246, s[16:17] offset:0 nt
	global_load_dwordx4 v[36:39], v242, s[12:13] offset:1024 nt
	global_load_dwordx2 v[82:83], v246, s[16:17] offset:512 nt
	global_load_dwordx4 v[40:43], v242, s[12:13] offset:2048 nt
	global_load_dwordx2 v[84:85], v246, s[16:17] offset:1024 nt
	global_load_dwordx4 v[44:47], v242, s[12:13] offset:3072 nt
	global_load_dwordx2 v[86:87], v246, s[16:17] offset:1536 nt
	global_load_dwordx4 v[48:51], v243, s[12:13] offset:0 nt
	global_load_dwordx2 v[88:89], v247, s[16:17] offset:0 nt
	global_load_dwordx4 v[52:55], v243, s[12:13] offset:1024 nt
	global_load_dwordx2 v[90:91], v247, s[16:17] offset:512 nt
	global_load_dwordx4 v[56:59], v243, s[12:13] offset:2048 nt
	global_load_dwordx2 v[92:93], v247, s[16:17] offset:1024 nt
	global_load_dwordx4 v[60:63], v243, s[12:13] offset:3072 nt
	global_load_dwordx2 v[94:95], v247, s[16:17] offset:1536 nt
	v_mov_b32_e32 v248, 0
	s_waitcnt vmcnt(30)
	v_lshlrev_b32_e32 v96, 16, v64
	v_and_b32_e32 v97, 0xffff0000, v64
	v_lshlrev_b32_e32 v98, 16, v65
	v_and_b32_e32 v99, 0xffff0000, v65
	v_fma_f32 v0, s7, v0, v96
	v_fma_f32 v1, s7, v1, v97
	v_fma_f32 v2, s7, v2, v98
	v_fma_f32 v3, s7, v3, v99
	v_add_f32_e32 v100, v0, v1
	v_add_f32_e32 v100, v100, v2
	v_add_f32_e32 v100, v100, v3
	v_add_f32_e32 v248, v248, v100
	s_waitcnt vmcnt(28)
	v_lshlrev_b32_e32 v96, 16, v66
	v_and_b32_e32 v97, 0xffff0000, v66
	v_lshlrev_b32_e32 v98, 16, v67
	v_and_b32_e32 v99, 0xffff0000, v67
	v_fma_f32 v4, s7, v4, v96
	v_fma_f32 v5, s7, v5, v97
	v_fma_f32 v6, s7, v6, v98
	v_fma_f32 v7, s7, v7, v99
	v_add_f32_e32 v100, v4, v5
	v_add_f32_e32 v100, v100, v6
	v_add_f32_e32 v100, v100, v7
	v_add_f32_e32 v248, v248, v100
	s_waitcnt vmcnt(26)
; __device__ void phase_ln(const Params& p) {
;     ...
; #pragma unroll
;     for (int i = 0; i < 16; ++i) { const f32x4 xv = __builtin_nontemporal_load(reinterpret_cast<const f32x4*>(xr + i * 256 + lane * 4));
;       const u32x2 hw = __builtin_nontemporal_load(reinterpret_cast<const u32x2*>(hr + i * 256 + lane * 4));
;       v[i][0] = fmaf(ALPHA, xv[0], __uint_as_float(hw[0] << 16)); v[i][1] = fmaf(ALPHA, xv[1], __uint_as_float(hw[0] & 0xffff0000u));
;       v[i][2] = fmaf(ALPHA, xv[2], __uint_as_float(hw[1] << 16)); v[i][3] = fmaf(ALPHA, xv[3], __uint_as_float(hw[1] & 0xffff0000u));
;       s += v[i][0] + v[i][1] + v[i][2] + v[i][3]; }
	v_lshlrev_b32_e32 v96, 16, v68
	v_and_b32_e32 v97, 0xffff0000, v68
	v_lshlrev_b32_e32 v98, 16, v69
	v_and_b32_e32 v99, 0xffff0000, v69
	v_fma_f32 v8, s7, v8, v96
	v_fma_f32 v9, s7, v9, v97
	v_fma_f32 v10, s7, v10, v98
	v_fma_f32 v11, s7, v11, v99
	v_add_f32_e32 v100, v8, v9
	v_add_f32_e32 v100, v100, v10
	v_add_f32_e32 v100, v100, v11
	v_add_f32_e32 v248, v248, v100
	s_waitcnt vmcnt(24)
	v_lshlrev_b32_e32 v96, 16, v70
	v_and_b32_e32 v97, 0xffff0000, v70
	v_lshlrev_b32_e32 v98, 16, v71
	v_and_b32_e32 v99, 0xffff0000, v71
	v_fma_f32 v12, s7, v12, v96
	v_fma_f32 v13, s7, v13, v97
	v_fma_f32 v14, s7, v14, v98
	v_fma_f32 v15, s7, v15, v99
	v_add_f32_e32 v100, v12, v13
	v_add_f32_e32 v100, v100, v14
	v_add_f32_e32 v100, v100, v15
	v_add_f32_e32 v248, v248, v100
	s_waitcnt vmcnt(22)
	v_lshlrev_b32_e32 v96, 16, v72
	v_and_b32_e32 v97, 0xffff0000, v72
	v_lshlrev_b32_e32 v98, 16, v73
	v_and_b32_e32 v99, 0xffff0000, v73
	v_fma_f32 v16, s7, v16, v96
	v_fma_f32 v17, s7, v17, v97
	v_fma_f32 v18, s7, v18, v98
	v_fma_f32 v19, s7, v19, v99
	v_add_f32_e32 v100, v16, v17
	v_add_f32_e32 v100, v100, v18
	v_add_f32_e32 v100, v100, v19
	v_add_f32_e32 v248, v248, v100
	s_waitcnt vmcnt(20)
	v_lshlrev_b32_e32 v96, 16, v74
	v_and_b32_e32 v97, 0xffff0000, v74
	v_lshlrev_b32_e32 v98, 16, v75
	v_and_b32_e32 v99, 0xffff0000, v75
	v_fma_f32 v20, s7, v20, v96
	v_fma_f32 v21, s7, v21, v97
	v_fma_f32 v22, s7, v22, v98
	v_fma_f32 v23, s7, v23, v99
	v_add_f32_e32 v100, v20, v21
	v_add_f32_e32 v100, v100, v22
	v_add_f32_e32 v100, v100, v23
	v_add_f32_e32 v248, v248, v100
	s_waitcnt vmcnt(18)
	v_lshlrev_b32_e32 v96, 16, v76
	v_and_b32_e32 v97, 0xffff0000, v76
	v_lshlrev_b32_e32 v98, 16, v77
	v_and_b32_e32 v99, 0xffff0000, v77
	v_fma_f32 v24, s7, v24, v96
	v_fma_f32 v25, s7, v25, v97
	v_fma_f32 v26, s7, v26, v98
	v_fma_f32 v27, s7, v27, v99
	v_add_f32_e32 v100, v24, v25
	v_add_f32_e32 v100, v100, v26
	v_add_f32_e32 v100, v100, v27
	v_add_f32_e32 v248, v248, v100
	s_waitcnt vmcnt(16)
	v_lshlrev_b32_e32 v96, 16, v78
	v_and_b32_e32 v97, 0xffff0000, v78
	v_lshlrev_b32_e32 v98, 16, v79
	v_and_b32_e32 v99, 0xffff0000, v79
	v_fma_f32 v28, s7, v28, v96
	v_fma_f32 v29, s7, v29, v97
	v_fma_f32 v30, s7, v30, v98
	v_fma_f32 v31, s7, v31, v99
	v_add_f32_e32 v100, v28, v29
	v_add_f32_e32 v100, v100, v30
	v_add_f32_e32 v100, v100, v31
	v_add_f32_e32 v248, v248, v100
	s_waitcnt vmcnt(14)
	v_lshlrev_b32_e32 v96, 16, v80
	v_and_b32_e32 v97, 0xffff0000, v80
	v_lshlrev_b32_e32 v98, 16, v81
	v_and_b32_e32 v99, 0xffff0000, v81
	v_fma_f32 v32, s7, v32, v96
	v_fma_f32 v33, s7, v33, v97
	v_fma_f32 v34, s7, v34, v98
	v_fma_f32 v35, s7, v35, v99
	v_add_f32_e32 v100, v32, v33
	v_add_f32_e32 v100, v100, v34
	v_add_f32_e32 v100, v100, v35
	v_add_f32_e32 v248, v248, v100
	s_waitcnt vmcnt(12)
	v_lshlrev_b32_e32 v96, 16, v82
	v_and_b32_e32 v97, 0xffff0000, v82
	v_lshlrev_b32_e32 v98, 16, v83
	v_and_b32_e32 v99, 0xffff0000, v83
	v_fma_f32 v36, s7, v36, v96
	v_fma_f32 v37, s7, v37, v97
	v_fma_f32 v38, s7, v38, v98
	v_fma_f32 v39, s7, v39, v99
	v_add_f32_e32 v100, v36, v37
	v_add_f32_e32 v100, v100, v38
	v_add_f32_e32 v100, v100, v39
	v_add_f32_e32 v248, v248, v100
	s_waitcnt vmcnt(10)
	v_lshlrev_b32_e32 v96, 16, v84
	v_and_b32_e32 v97, 0xffff0000, v84
	v_lshlrev_b32_e32 v98, 16, v85
	v_and_b32_e32 v99, 0xffff0000, v85
	v_fma_f32 v40, s7, v40, v96
	v_fma_f32 v41, s7, v41, v97
	v_fma_f32 v42, s7, v42, v98
	v_fma_f32 v43, s7, v43, v99
	v_add_f32_e32 v100, v40, v41
	v_add_f32_e32 v100, v100, v42
	v_add_f32_e32 v100, v100, v43
	v_add_f32_e32 v248, v248, v100
	s_waitcnt vmcnt(8)
	v_lshlrev_b32_e32 v96, 16, v86
	v_and_b32_e32 v97, 0xffff0000, v86
	v_lshlrev_b32_e32 v98, 16, v87
	v_and_b32_e32 v99, 0xffff0000, v87
	v_fma_f32 v44, s7, v44, v96
	v_fma_f32 v45, s7, v45, v97
	v_fma_f32 v46, s7, v46, v98
	v_fma_f32 v47, s7, v47, v99
	v_add_f32_e32 v100, v44, v45
	v_add_f32_e32 v100, v100, v46
	v_add_f32_e32 v100, v100, v47
	v_add_f32_e32 v248, v248, v100
	s_waitcnt vmcnt(6)
	v_lshlrev_b32_e32 v96, 16, v88
	v_and_b32_e32 v97, 0xffff0000, v88
	v_lshlrev_b32_e32 v98, 16, v89
	v_and_b32_e32 v99, 0xffff0000, v89
	v_fma_f32 v48, s7, v48, v96
	v_fma_f32 v49, s7, v49, v97
	v_fma_f32 v50, s7, v50, v98
	v_fma_f32 v51, s7, v51, v99
	v_add_f32_e32 v100, v48, v49
	v_add_f32_e32 v100, v100, v50
	v_add_f32_e32 v100, v100, v51
	v_add_f32_e32 v248, v248, v100
	s_waitcnt vmcnt(4)
	v_lshlrev_b32_e32 v96, 16, v90
	v_and_b32_e32 v97, 0xffff0000, v90
	v_lshlrev_b32_e32 v98, 16, v91
	v_and_b32_e32 v99, 0xffff0000, v91
	v_fma_f32 v52, s7, v52, v96
	v_fma_f32 v53, s7, v53, v97
	v_fma_f32 v54, s7, v54, v98
	v_fma_f32 v55, s7, v55, v99
	v_add_f32_e32 v100, v52, v53
	v_add_f32_e32 v100, v100, v54
	v_add_f32_e32 v100, v100, v55
	v_add_f32_e32 v248, v248, v100
	s_waitcnt vmcnt(2)
	v_lshlrev_b32_e32 v96, 16, v92
	v_and_b32_e32 v97, 0xffff0000, v92
	v_lshlrev_b32_e32 v98, 16, v93
	v_and_b32_e32 v99, 0xffff0000, v93
	v_fma_f32 v56, s7, v56, v96
	v_fma_f32 v57, s7, v57, v97
	v_fma_f32 v58, s7, v58, v98
	v_fma_f32 v59, s7, v59, v99
	v_add_f32_e32 v100, v56, v57
	v_add_f32_e32 v100, v100, v58
	v_add_f32_e32 v100, v100, v59
	v_add_f32_e32 v248, v248, v100
	s_waitcnt vmcnt(0)
; __device__ void phase_ln(const Params& p) {
;     ...
;       s += v[i][0] + v[i][1] + v[i][2] + v[i][3]; }
; #pragma unroll
;     for (int o = 32; o > 0; o >>= 1) s += __shfl_xor(s, o);
;     const float mu = s * (1.f / DM); float q = 0.f;
; #pragma unroll
;     for (int i = 0; i < 16; ++i) { for (int j = 0; j < 4; ++j) { float d = v[i][j] - mu; q += d * d; } }
; #pragma unroll
;     for (int o = 32; o > 0; o >>= 1) q += __shfl_xor(q, o);
;     const float rs = rsqrtf(q * (1.f / DM) + 1e-5f);
	v_lshlrev_b32_e32 v96, 16, v94
	v_and_b32_e32 v97, 0xffff0000, v94
	v_lshlrev_b32_e32 v98, 16, v95
	v_and_b32_e32 v99, 0xffff0000, v95
	v_fma_f32 v60, s7, v60, v96
	v_fma_f32 v61, s7, v61, v97
	v_fma_f32 v62, s7, v62, v98
	v_fma_f32 v63, s7, v63, v99
	v_add_f32_e32 v100, v60, v61
	v_add_f32_e32 v100, v100, v62
	v_add_f32_e32 v100, v100, v63
	v_add_f32_e32 v248, v248, v100
	s_nop 1
	v_add_f32_dpp v100, v248, v248 quad_perm:[1,0,3,2] row_mask:0xf bank_mask:0xf bound_ctrl:1
	s_nop 1
	v_add_f32_dpp v101, v100, v100 quad_perm:[2,3,0,1] row_mask:0xf bank_mask:0xf bound_ctrl:1
	s_nop 1
	v_add_f32_dpp v102, v101, v101 row_half_mirror row_mask:0xf bank_mask:0xf bound_ctrl:1
	s_nop 1
	v_add_f32_dpp v103, v102, v102 row_mirror row_mask:0xf bank_mask:0xf bound_ctrl:1
	s_nop 1
	v_readlane_b32 s20, v103, 0
	v_readlane_b32 s21, v103, 16
	v_readlane_b32 s22, v103, 32
	v_readlane_b32 s23, v103, 48
	s_nop 1
	v_mov_b32_e32 v249, s20
	v_add_f32_e32 v249, s21, v249
	v_add_f32_e32 v249, s22, v249
	v_add_f32_e32 v249, s23, v249
	v_mul_f32_e32 v249, 0x39800000, v249
	v_mov_b32_e32 v250, 0
	v_sub_f32_e32 v0, v0, v249
	v_fmac_f32_e32 v250, v0, v0
	v_sub_f32_e32 v1, v1, v249
	v_fmac_f32_e32 v250, v1, v1
	v_sub_f32_e32 v2, v2, v249
	v_fmac_f32_e32 v250, v2, v2
	v_sub_f32_e32 v3, v3, v249
	v_fmac_f32_e32 v250, v3, v3
	v_sub_f32_e32 v4, v4, v249
	v_fmac_f32_e32 v250, v4, v4
	v_sub_f32_e32 v5, v5, v249
	v_fmac_f32_e32 v250, v5, v5
	v_sub_f32_e32 v6, v6, v249
	v_fmac_f32_e32 v250, v6, v6
	v_sub_f32_e32 v7, v7, v249
	v_fmac_f32_e32 v250, v7, v7
	v_sub_f32_e32 v8, v8, v249
	v_fmac_f32_e32 v250, v8, v8
	v_sub_f32_e32 v9, v9, v249
	v_fmac_f32_e32 v250, v9, v9
	v_sub_f32_e32 v10, v10, v249
	v_fmac_f32_e32 v250, v10, v10
	v_sub_f32_e32 v11, v11, v249
	v_fmac_f32_e32 v250, v11, v11
	v_sub_f32_e32 v12, v12, v249
	v_fmac_f32_e32 v250, v12, v12
	v_sub_f32_e32 v13, v13, v249
	v_fmac_f32_e32 v250, v13, v13
	v_sub_f32_e32 v14, v14, v249
	v_fmac_f32_e32 v250, v14, v14
	v_sub_f32_e32 v15, v15, v249
	v_fmac_f32_e32 v250, v15, v15
	v_sub_f32_e32 v16, v16, v249
	v_fmac_f32_e32 v250, v16, v16
	v_sub_f32_e32 v17, v17, v249
	v_fmac_f32_e32 v250, v17, v17
	v_sub_f32_e32 v18, v18, v249
	v_fmac_f32_e32 v250, v18, v18
	v_sub_f32_e32 v19, v19, v249
	v_fmac_f32_e32 v250, v19, v19
	v_sub_f32_e32 v20, v20, v249
	v_fmac_f32_e32 v250, v20, v20
	v_sub_f32_e32 v21, v21, v249
	v_fmac_f32_e32 v250, v21, v21
	v_sub_f32_e32 v22, v22, v249
	v_fmac_f32_e32 v250, v22, v22
	v_sub_f32_e32 v23, v23, v249
	v_fmac_f32_e32 v250, v23, v23
	v_sub_f32_e32 v24, v24, v249
	v_fmac_f32_e32 v250, v24, v24
	v_sub_f32_e32 v25, v25, v249
	v_fmac_f32_e32 v250, v25, v25
	v_sub_f32_e32 v26, v26, v249
	v_fmac_f32_e32 v250, v26, v26
	v_sub_f32_e32 v27, v27, v249
	v_fmac_f32_e32 v250, v27, v27
	v_sub_f32_e32 v28, v28, v249
	v_fmac_f32_e32 v250, v28, v28
	v_sub_f32_e32 v29, v29, v249
	v_fmac_f32_e32 v250, v29, v29
	v_sub_f32_e32 v30, v30, v249
	v_fmac_f32_e32 v250, v30, v30
	v_sub_f32_e32 v31, v31, v249
	v_fmac_f32_e32 v250, v31, v31
	v_sub_f32_e32 v32, v32, v249
	v_fmac_f32_e32 v250, v32, v32
	v_sub_f32_e32 v33, v33, v249
	v_fmac_f32_e32 v250, v33, v33
	v_sub_f32_e32 v34, v34, v249
	v_fmac_f32_e32 v250, v34, v34
	v_sub_f32_e32 v35, v35, v249
	v_fmac_f32_e32 v250, v35, v35
	v_sub_f32_e32 v36, v36, v249
	v_fmac_f32_e32 v250, v36, v36
	v_sub_f32_e32 v37, v37, v249
	v_fmac_f32_e32 v250, v37, v37
	v_sub_f32_e32 v38, v38, v249
	v_fmac_f32_e32 v250, v38, v38
	v_sub_f32_e32 v39, v39, v249
	v_fmac_f32_e32 v250, v39, v39
	v_sub_f32_e32 v40, v40, v249
	v_fmac_f32_e32 v250, v40, v40
	v_sub_f32_e32 v41, v41, v249
	v_fmac_f32_e32 v250, v41, v41
	v_sub_f32_e32 v42, v42, v249
	v_fmac_f32_e32 v250, v42, v42
	v_sub_f32_e32 v43, v43, v249
	v_fmac_f32_e32 v250, v43, v43
	v_sub_f32_e32 v44, v44, v249
	v_fmac_f32_e32 v250, v44, v44
	v_sub_f32_e32 v45, v45, v249
	v_fmac_f32_e32 v250, v45, v45
	v_sub_f32_e32 v46, v46, v249
	v_fmac_f32_e32 v250, v46, v46
	v_sub_f32_e32 v47, v47, v249
	v_fmac_f32_e32 v250, v47, v47
	v_sub_f32_e32 v48, v48, v249
	v_fmac_f32_e32 v250, v48, v48
	v_sub_f32_e32 v49, v49, v249
	v_fmac_f32_e32 v250, v49, v49
	v_sub_f32_e32 v50, v50, v249
	v_fmac_f32_e32 v250, v50, v50
	v_sub_f32_e32 v51, v51, v249
	v_fmac_f32_e32 v250, v51, v51
	v_sub_f32_e32 v52, v52, v249
	v_fmac_f32_e32 v250, v52, v52
	v_sub_f32_e32 v53, v53, v249
	v_fmac_f32_e32 v250, v53, v53
	v_sub_f32_e32 v54, v54, v249
	v_fmac_f32_e32 v250, v54, v54
	v_sub_f32_e32 v55, v55, v249
	v_fmac_f32_e32 v250, v55, v55
	v_sub_f32_e32 v56, v56, v249
	v_fmac_f32_e32 v250, v56, v56
	v_sub_f32_e32 v57, v57, v249
	v_fmac_f32_e32 v250, v57, v57
	v_sub_f32_e32 v58, v58, v249
	v_fmac_f32_e32 v250, v58, v58
	v_sub_f32_e32 v59, v59, v249
	v_fmac_f32_e32 v250, v59, v59
	v_sub_f32_e32 v60, v60, v249
	v_fmac_f32_e32 v250, v60, v60
	v_sub_f32_e32 v61, v61, v249
	v_fmac_f32_e32 v250, v61, v61
	v_sub_f32_e32 v62, v62, v249
	v_fmac_f32_e32 v250, v62, v62
	v_sub_f32_e32 v63, v63, v249
	v_fmac_f32_e32 v250, v63, v63
	s_nop 1
	v_add_f32_dpp v100, v250, v250 quad_perm:[1,0,3,2] row_mask:0xf bank_mask:0xf bound_ctrl:1
	s_nop 1
	v_add_f32_dpp v101, v100, v100 quad_perm:[2,3,0,1] row_mask:0xf bank_mask:0xf bound_ctrl:1
	s_nop 1
	v_add_f32_dpp v102, v101, v101 row_half_mirror row_mask:0xf bank_mask:0xf bound_ctrl:1
	s_nop 1
	v_add_f32_dpp v103, v102, v102 row_mirror row_mask:0xf bank_mask:0xf bound_ctrl:1
; __device__ void phase_ln(const Params& p) {
;     ...
;     for (int o = 32; o > 0; o >>= 1) q += __shfl_xor(q, o);
;     const float rs = rsqrtf(q * (1.f / DM) + 1e-5f);
; #pragma unroll
;     for (int i = 0; i < 16; ++i) {
;       f32x4 g = *reinterpret_cast<const f32x4*>(p.ln_g + i * 256 + lane * 4), b = *reinterpret_cast<const f32x4*>(p.ln_b + i * 256 + lane * 4);
;       f32x4 o = {(v[i][0] - mu) * rs * g[0] + b[0], (v[i][1] - mu) * rs * g[1] + b[1], (v[i][2] - mu) * rs * g[2] + b[2], (v[i][3] - mu) * rs * g[3] + b[3]};
;       __builtin_nontemporal_store(o, reinterpret_cast<f32x4*>(r + i * 256 + lane * 4));
;     }
	s_nop 1
	v_readlane_b32 s20, v103, 0
	v_readlane_b32 s21, v103, 16
	v_readlane_b32 s22, v103, 32
	v_readlane_b32 s23, v103, 48
	s_nop 1
	v_mov_b32_e32 v251, s20
	v_add_f32_e32 v251, s21, v251
	v_add_f32_e32 v251, s22, v251
	v_add_f32_e32 v251, s23, v251
	v_fmamk_f32 v251, v251, 0x39800000, v104
	v_rsq_f32_e32 v251, v251
	s_nop 0
	v_mul_f32_e32 v0, v0, v251
	v_mul_f32_e32 v1, v1, v251
	v_mul_f32_e32 v2, v2, v251
	v_mul_f32_e32 v3, v3, v251
	v_fma_f32 v0, v0, v112, v176
	v_fma_f32 v1, v1, v113, v177
	v_fma_f32 v2, v2, v114, v178
	v_fma_f32 v3, v3, v115, v179
	global_store_dwordx4 v240, v[0:3], s[14:15] offset:0 nt
	v_mul_f32_e32 v4, v4, v251
	v_mul_f32_e32 v5, v5, v251
	v_mul_f32_e32 v6, v6, v251
	v_mul_f32_e32 v7, v7, v251
	v_fma_f32 v4, v4, v116, v180
	v_fma_f32 v5, v5, v117, v181
	v_fma_f32 v6, v6, v118, v182
	v_fma_f32 v7, v7, v119, v183
	global_store_dwordx4 v240, v[4:7], s[14:15] offset:1024 nt
	v_mul_f32_e32 v8, v8, v251
	v_mul_f32_e32 v9, v9, v251
	v_mul_f32_e32 v10, v10, v251
	v_mul_f32_e32 v11, v11, v251
	v_fma_f32 v8, v8, v120, v184
	v_fma_f32 v9, v9, v121, v185
	v_fma_f32 v10, v10, v122, v186
	v_fma_f32 v11, v11, v123, v187
	global_store_dwordx4 v240, v[8:11], s[14:15] offset:2048 nt
	v_mul_f32_e32 v12, v12, v251
	v_mul_f32_e32 v13, v13, v251
	v_mul_f32_e32 v14, v14, v251
	v_mul_f32_e32 v15, v15, v251
	v_fma_f32 v12, v12, v124, v188
	v_fma_f32 v13, v13, v125, v189
	v_fma_f32 v14, v14, v126, v190
	v_fma_f32 v15, v15, v127, v191
	global_store_dwordx4 v240, v[12:15], s[14:15] offset:3072 nt
	v_mul_f32_e32 v16, v16, v251
	v_mul_f32_e32 v17, v17, v251
	v_mul_f32_e32 v18, v18, v251
	v_mul_f32_e32 v19, v19, v251
	v_fma_f32 v16, v16, v128, v192
	v_fma_f32 v17, v17, v129, v193
	v_fma_f32 v18, v18, v130, v194
	v_fma_f32 v19, v19, v131, v195
	global_store_dwordx4 v241, v[16:19], s[14:15] offset:0 nt
	v_mul_f32_e32 v20, v20, v251
	v_mul_f32_e32 v21, v21, v251
	v_mul_f32_e32 v22, v22, v251
	v_mul_f32_e32 v23, v23, v251
	v_fma_f32 v20, v20, v132, v196
	v_fma_f32 v21, v21, v133, v197
	v_fma_f32 v22, v22, v134, v198
	v_fma_f32 v23, v23, v135, v199
	global_store_dwordx4 v241, v[20:23], s[14:15] offset:1024 nt
	v_mul_f32_e32 v24, v24, v251
	v_mul_f32_e32 v25, v25, v251
	v_mul_f32_e32 v26, v26, v251
	v_mul_f32_e32 v27, v27, v251
	v_fma_f32 v24, v24, v136, v200
	v_fma_f32 v25, v25, v137, v201
	v_fma_f32 v26, v26, v138, v202
	v_fma_f32 v27, v27, v139, v203
	global_store_dwordx4 v241, v[24:27], s[14:15] offset:2048 nt
	v_mul_f32_e32 v28, v28, v251
	v_mul_f32_e32 v29, v29, v251
	v_mul_f32_e32 v30, v30, v251
	v_mul_f32_e32 v31, v31, v251
	v_fma_f32 v28, v28, v140, v204
	v_fma_f32 v29, v29, v141, v205
	v_fma_f32 v30, v30, v142, v206
	v_fma_f32 v31, v31, v143, v207
	global_store_dwordx4 v241, v[28:31], s[14:15] offset:3072 nt
	v_mul_f32_e32 v32, v32, v251
	v_mul_f32_e32 v33, v33, v251
	v_mul_f32_e32 v34, v34, v251
	v_mul_f32_e32 v35, v35, v251
	v_fma_f32 v32, v32, v144, v208
	v_fma_f32 v33, v33, v145, v209
	v_fma_f32 v34, v34, v146, v210
	v_fma_f32 v35, v35, v147, v211
	global_store_dwordx4 v242, v[32:35], s[14:15] offset:0 nt
	v_mul_f32_e32 v36, v36, v251
	v_mul_f32_e32 v37, v37, v251
	v_mul_f32_e32 v38, v38, v251
	v_mul_f32_e32 v39, v39, v251
	v_fma_f32 v36, v36, v148, v212
	v_fma_f32 v37, v37, v149, v213
	v_fma_f32 v38, v38, v150, v214
	v_fma_f32 v39, v39, v151, v215
	global_store_dwordx4 v242, v[36:39], s[14:15] offset:1024 nt
	v_mul_f32_e32 v40, v40, v251
	v_mul_f32_e32 v41, v41, v251
	v_mul_f32_e32 v42, v42, v251
	v_mul_f32_e32 v43, v43, v251
	v_fma_f32 v40, v40, v152, v216
	v_fma_f32 v41, v41, v153, v217
	v_fma_f32 v42, v42, v154, v218
	v_fma_f32 v43, v43, v155, v219
	global_store_dwordx4 v242, v[40:43], s[14:15] offset:2048 nt
	v_mul_f32_e32 v44, v44, v251
	v_mul_f32_e32 v45, v45, v251
	v_mul_f32_e32 v46, v46, v251
	v_mul_f32_e32 v47, v47, v251
	v_fma_f32 v44, v44, v156, v220
	v_fma_f32 v45, v45, v157, v221
	v_fma_f32 v46, v46, v158, v222
	v_fma_f32 v47, v47, v159, v223
	global_store_dwordx4 v242, v[44:47], s[14:15] offset:3072 nt
	v_mul_f32_e32 v48, v48, v251
	v_mul_f32_e32 v49, v49, v251
	v_mul_f32_e32 v50, v50, v251
	v_mul_f32_e32 v51, v51, v251
	v_fma_f32 v48, v48, v160, v224
	v_fma_f32 v49, v49, v161, v225
	v_fma_f32 v50, v50, v162, v226
	v_fma_f32 v51, v51, v163, v227
	global_store_dwordx4 v243, v[48:51], s[14:15] offset:0 nt
	v_mul_f32_e32 v52, v52, v251
	v_mul_f32_e32 v53, v53, v251
	v_mul_f32_e32 v54, v54, v251
	v_mul_f32_e32 v55, v55, v251
	v_fma_f32 v52, v52, v164, v228
	v_fma_f32 v53, v53, v165, v229
	v_fma_f32 v54, v54, v166, v230
	v_fma_f32 v55, v55, v167, v231
	global_store_dwordx4 v243, v[52:55], s[14:15] offset:1024 nt
	v_mul_f32_e32 v56, v56, v251
	v_mul_f32_e32 v57, v57, v251
	v_mul_f32_e32 v58, v58, v251
	v_mul_f32_e32 v59, v59, v251
	v_fma_f32 v56, v56, v168, v232
	v_fma_f32 v57, v57, v169, v233
	v_fma_f32 v58, v58, v170, v234
	v_fma_f32 v59, v59, v171, v235
	global_store_dwordx4 v243, v[56:59], s[14:15] offset:2048 nt
	v_mul_f32_e32 v60, v60, v251
	v_mul_f32_e32 v61, v61, v251
	v_mul_f32_e32 v62, v62, v251
	v_mul_f32_e32 v63, v63, v251
	v_fma_f32 v60, v60, v172, v236
	v_fma_f32 v61, v61, v173, v237
	v_fma_f32 v62, v62, v174, v238
	v_fma_f32 v63, v63, v175, v239
	global_store_dwordx4 v243, v[60:63], s[14:15] offset:3072 nt
	s_add_u32 s4, s4, s5
	s_cmpk_lt_u32 s4, 0x4000
	s_cbranch_scc1 .Lln_row
